# bias-in-LDS plus mixer-A MIX stores sc1 (write-through)
# baseline (speedup 1.0000x reference)
.LBB0_338:
	v_add_u32_e32 v128, s87, v234
	v_ashrrev_i32_e32 v129, 31, v128
	v_lshl_add_u64 v[168:169], v[128:129], 2, s[56:57]
	v_lshl_add_u32 v130, v233, 2, s32
	ds_read_b32 v130, v130
	v_lshlrev_b32_e32 v131, 16, v127
	v_and_b32_e32 v127, 0xffff0000, v127
	v_lshlrev_b32_e32 v132, 16, v126
	v_and_b32_e32 v126, 0xffff0000, v126
	v_lshlrev_b32_e32 v133, 16, v125
	v_and_b32_e32 v125, 0xffff0000, v125
	v_lshlrev_b32_e32 v134, 16, v124
	v_and_b32_e32 v124, 0xffff0000, v124
	v_add_u32_e32 v171, s99, v212
	v_add_u32_e32 v128, s94, v234
	v_ashrrev_i32_e32 v129, 31, v128
	s_and_b64 vcc, exec, s[8:9]
	s_waitcnt vmcnt(0) lgkmcnt(0)
	v_fma_f32 v64, v116, v64, v130
	v_fma_f32 v65, v117, v65, v130
	v_fma_f32 v66, v118, v66, v130
	v_fma_f32 v67, v119, v67, v130
	v_fma_f32 v68, v112, v68, v130
	v_fma_f32 v69, v113, v69, v130
	v_fma_f32 v70, v114, v70, v130
	v_fmac_f32_e32 v130, v115, v71
	v_mul_f32_e32 v64, v64, v131
	v_mul_f32_e32 v65, v65, v127
	v_mul_f32_e32 v66, v66, v132
	v_mul_f32_e32 v67, v67, v126
	v_mul_f32_e32 v68, v68, v133
	v_mul_f32_e32 v69, v69, v125
	v_mul_f32_e32 v70, v70, v134
	v_mul_f32_e32 v71, v130, v124
	v_cvt_pk_bf16_f32 v64, v64, v65
	v_cvt_pk_bf16_f32 v65, v66, v67
	v_cvt_pk_bf16_f32 v66, v68, v69
	v_cvt_pk_bf16_f32 v67, v70, v71
	ds_read_b128 v[68:71], v171 offset:256
	v_lshlrev_b64 v[124:125], 12, v[128:129]
	v_lshl_add_u64 v[124:125], s[12:13], 0, v[124:125]
	v_lshl_add_u64 v[124:125], v[228:229], 1, v[124:125]
	global_store_dwordx4 v[124:125], v[64:67], off sc1
	s_waitcnt lgkmcnt(0)
	s_nop 0
	v_lshlrev_b32_e32 v64, 16, v68
	v_and_b32_e32 v65, 0xffff0000, v68
	v_lshlrev_b32_e32 v66, 16, v69
	v_and_b32_e32 v67, 0xffff0000, v69
	v_lshlrev_b32_e32 v68, 16, v70
	v_and_b32_e32 v69, 0xffff0000, v70
	v_lshlrev_b32_e32 v70, 16, v71
	v_and_b32_e32 v71, 0xffff0000, v71
	v_mul_f32_e32 v64, v88, v64
	v_mul_f32_e32 v65, v90, v65
	v_mul_f32_e32 v66, v92, v66
	v_mul_f32_e32 v67, v94, v67
	v_mul_f32_e32 v68, v87, v68
	v_mul_f32_e32 v69, v89, v69
	v_mul_f32_e32 v70, v91, v70
	v_mul_f32_e32 v71, v93, v71
	v_cvt_pk_bf16_f32 v64, v64, v65
	v_cvt_pk_bf16_f32 v65, v66, v67
	v_cvt_pk_bf16_f32 v66, v68, v69
	v_cvt_pk_bf16_f32 v67, v70, v71
	s_nop 0
	v_mfma_f32_16x16x32_bf16 v[68:71], v[164:167], v[64:67], 0
	v_mfma_f32_16x16x32_bf16 v[64:67], v[160:163], v[64:67], 0
	s_cbranch_vccz .LBB0_353
	s_and_b64 vcc, exec, s[8:9]
	s_cbranch_vccz .LBB0_354

.LBB0_342:
	v_lshl_add_u32 v125, v233, 2, s32
	ds_read_b32 v125, v125 offset:64
	v_lshlrev_b32_e32 v126, 16, v123
	v_and_b32_e32 v123, 0xffff0000, v123
	v_add_u32_e32 v124, s94, v240
	v_add_u32_e32 v170, s43, v212
	s_and_b64 vcc, exec, s[8:9]
	s_waitcnt lgkmcnt(0)
	v_fma_f32 v68, v116, v68, v125
	v_fma_f32 v69, v117, v69, v125
	v_mul_f32_e32 v68, v68, v126
	v_mul_f32_e32 v69, v69, v123
	v_cvt_pk_bf16_f32 v68, v68, v69
	v_lshlrev_b32_e32 v69, 16, v122
	v_fma_f32 v70, v118, v70, v125
	v_mul_f32_e32 v69, v70, v69
	v_and_b32_e32 v70, 0xffff0000, v122
	v_fma_f32 v71, v119, v71, v125
	v_mul_f32_e32 v70, v71, v70
	v_cvt_pk_bf16_f32 v69, v69, v70
	v_lshlrev_b32_e32 v70, 16, v121
	v_fma_f32 v64, v112, v64, v125
	v_mul_f32_e32 v64, v64, v70
	v_and_b32_e32 v70, 0xffff0000, v121
	v_fma_f32 v65, v113, v65, v125
	v_mul_f32_e32 v65, v65, v70
	v_cvt_pk_bf16_f32 v70, v64, v65
	v_lshlrev_b32_e32 v64, 16, v120
	v_fma_f32 v65, v114, v66, v125
	v_mul_f32_e32 v64, v65, v64
	v_and_b32_e32 v65, 0xffff0000, v120
	v_fmac_f32_e32 v125, v115, v67
	v_mul_f32_e32 v65, v125, v65
	v_ashrrev_i32_e32 v125, 31, v124
	v_cvt_pk_bf16_f32 v71, v64, v65
	v_lshlrev_b64 v[64:65], 12, v[124:125]
	v_lshl_add_u64 v[64:65], s[12:13], 0, v[64:65]
	v_lshl_add_u64 v[64:65], v[228:229], 1, v[64:65]
	global_store_dwordx4 v[64:65], v[68:71], off sc1
	ds_read_b128 v[64:67], v170
	s_waitcnt lgkmcnt(0)
	v_lshlrev_b32_e32 v68, 16, v64
	v_and_b32_e32 v64, 0xffff0000, v64
	v_mul_f32_e32 v68, v88, v68
	v_mul_f32_e32 v64, v90, v64
	v_cvt_pk_bf16_f32 v64, v68, v64
	v_lshlrev_b32_e32 v68, 16, v65
	v_and_b32_e32 v65, 0xffff0000, v65
	v_mul_f32_e32 v68, v92, v68
	v_mul_f32_e32 v65, v94, v65
	v_cvt_pk_bf16_f32 v65, v68, v65
	v_lshlrev_b32_e32 v68, 16, v66
	v_and_b32_e32 v66, 0xffff0000, v66
	v_mul_f32_e32 v68, v87, v68
	v_mul_f32_e32 v66, v89, v66
	v_cvt_pk_bf16_f32 v66, v68, v66
	v_lshlrev_b32_e32 v68, 16, v67
	v_and_b32_e32 v67, 0xffff0000, v67
	v_mul_f32_e32 v67, v93, v67
	v_mul_f32_e32 v68, v91, v68
	v_cvt_pk_bf16_f32 v67, v68, v67
	ds_read_b128 v[120:123], v170 offset:1024
	v_mfma_f32_16x16x32_bf16 v[68:71], v[164:167], v[64:67], 0
	s_waitcnt lgkmcnt(0)
	v_lshlrev_b32_e32 v124, 16, v120
	v_and_b32_e32 v120, 0xffff0000, v120
	v_mul_f32_e32 v124, v77, v124
	v_mul_f32_e32 v120, v79, v120
	v_cvt_pk_bf16_f32 v120, v124, v120
	v_lshlrev_b32_e32 v124, 16, v121
	v_and_b32_e32 v121, 0xffff0000, v121
	v_mul_f32_e32 v124, v84, v124
	v_mul_f32_e32 v121, v86, v121
	v_mfma_f32_16x16x32_bf16 v[64:67], v[160:163], v[64:67], 0
	v_cvt_pk_bf16_f32 v121, v124, v121
	v_lshlrev_b32_e32 v124, 16, v122
	v_and_b32_e32 v122, 0xffff0000, v122
	v_mul_f32_e32 v124, v76, v124
	v_mul_f32_e32 v122, v78, v122
	v_cvt_pk_bf16_f32 v122, v124, v122
	v_lshlrev_b32_e32 v124, 16, v123
	v_and_b32_e32 v123, 0xffff0000, v123
	v_mul_f32_e32 v123, v95, v123
	v_mul_f32_e32 v124, v85, v124
	v_cvt_pk_bf16_f32 v123, v124, v123
	s_nop 0
	v_mfma_f32_16x16x32_bf16 v[68:71], v[148:151], v[120:123], v[68:71]
	v_mfma_f32_16x16x32_bf16 v[64:67], v[144:147], v[120:123], v[64:67]
	s_cbranch_vccnz .LBB0_344
	ds_read_b128 v[120:123], v170 offset:2048
	s_waitcnt lgkmcnt(0)
	v_lshlrev_b32_e32 v124, 16, v120
	v_and_b32_e32 v120, 0xffff0000, v120
	v_mul_f32_e32 v124, v103, v124
	v_mul_f32_e32 v120, v102, v120
	v_cvt_pk_bf16_f32 v120, v124, v120
	v_lshlrev_b32_e32 v124, 16, v121
	v_and_b32_e32 v121, 0xffff0000, v121
	v_mul_f32_e32 v124, v101, v124
	v_mul_f32_e32 v121, v100, v121
	v_cvt_pk_bf16_f32 v121, v124, v121
	v_lshlrev_b32_e32 v124, 16, v122
	v_and_b32_e32 v122, 0xffff0000, v122
	v_mul_f32_e32 v124, v96, v124
	v_mul_f32_e32 v122, v97, v122
	v_cvt_pk_bf16_f32 v122, v124, v122
	v_lshlrev_b32_e32 v124, 16, v123
	v_and_b32_e32 v123, 0xffff0000, v123
	v_mul_f32_e32 v123, v99, v123
	v_mul_f32_e32 v124, v98, v124
	v_cvt_pk_bf16_f32 v123, v124, v123
	s_nop 0
	v_mfma_f32_16x16x32_bf16 v[68:71], v[140:143], v[120:123], v[68:71]
	v_mfma_f32_16x16x32_bf16 v[64:67], v[136:139], v[120:123], v[64:67]

.LBB0_346:
	v_lshl_add_u32 v122, v233, 2, s32
	ds_read_b32 v122, v122 offset:128
	v_lshlrev_b32_e32 v123, 16, v83
	v_and_b32_e32 v83, 0xffff0000, v83
	v_lshlrev_b32_e32 v124, 16, v82
	v_and_b32_e32 v82, 0xffff0000, v82
	v_lshlrev_b32_e32 v125, 16, v81
	v_and_b32_e32 v81, 0xffff0000, v81
	v_lshlrev_b32_e32 v126, 16, v80
	v_and_b32_e32 v80, 0xffff0000, v80
	v_add_u32_e32 v172, s75, v212
	v_add_u32_e32 v120, s94, v241
	v_ashrrev_i32_e32 v121, 31, v120
	s_and_b64 vcc, exec, s[8:9]
	s_waitcnt lgkmcnt(0)
	v_fma_f32 v68, v116, v68, v122
	v_fma_f32 v69, v117, v69, v122
	v_fma_f32 v70, v118, v70, v122
	v_fma_f32 v71, v119, v71, v122
	v_fma_f32 v64, v112, v64, v122
	v_fma_f32 v65, v113, v65, v122
	v_fma_f32 v66, v114, v66, v122
	v_fmac_f32_e32 v122, v115, v67
	v_mul_f32_e32 v67, v68, v123
	v_mul_f32_e32 v68, v69, v83
	v_mul_f32_e32 v69, v70, v124
	v_mul_f32_e32 v70, v71, v82
	v_mul_f32_e32 v71, v64, v125
	v_mul_f32_e32 v81, v65, v81
	v_mul_f32_e32 v82, v66, v126
	v_mul_f32_e32 v80, v122, v80
	v_cvt_pk_bf16_f32 v64, v67, v68
	v_cvt_pk_bf16_f32 v65, v69, v70
	v_cvt_pk_bf16_f32 v66, v71, v81
	v_cvt_pk_bf16_f32 v67, v82, v80
	ds_read_b128 v[68:71], v172 offset:256
	v_lshlrev_b64 v[80:81], 12, v[120:121]
	v_lshl_add_u64 v[80:81], s[12:13], 0, v[80:81]
	v_lshl_add_u64 v[80:81], v[228:229], 1, v[80:81]
	global_store_dwordx4 v[80:81], v[64:67], off sc1
	s_waitcnt lgkmcnt(0)
	s_nop 0
	v_lshlrev_b32_e32 v64, 16, v68
	v_and_b32_e32 v65, 0xffff0000, v68
	v_lshlrev_b32_e32 v66, 16, v69
	v_and_b32_e32 v67, 0xffff0000, v69
	v_lshlrev_b32_e32 v68, 16, v70
	v_and_b32_e32 v69, 0xffff0000, v70
	v_lshlrev_b32_e32 v70, 16, v71
	v_and_b32_e32 v71, 0xffff0000, v71
	v_mul_f32_e32 v64, v88, v64
	v_mul_f32_e32 v65, v90, v65
	v_mul_f32_e32 v66, v92, v66
	v_mul_f32_e32 v67, v94, v67
	v_mul_f32_e32 v68, v87, v68
	v_mul_f32_e32 v69, v89, v69
	v_mul_f32_e32 v70, v91, v70
	v_mul_f32_e32 v71, v93, v71
	v_cvt_pk_bf16_f32 v64, v64, v65
	v_cvt_pk_bf16_f32 v65, v66, v67
	v_cvt_pk_bf16_f32 v66, v68, v69
	v_cvt_pk_bf16_f32 v67, v70, v71
	ds_read_b128 v[80:83], v172 offset:1280
	v_mfma_f32_16x16x32_bf16 v[68:71], v[164:167], v[64:67], 0
	s_waitcnt lgkmcnt(0)
	v_lshlrev_b32_e32 v87, 16, v80
	v_mfma_f32_16x16x32_bf16 v[64:67], v[160:163], v[64:67], 0
	v_and_b32_e32 v80, 0xffff0000, v80
	v_lshlrev_b32_e32 v89, 16, v82
	v_and_b32_e32 v82, 0xffff0000, v82
	v_lshlrev_b32_e32 v88, 16, v81
	v_and_b32_e32 v81, 0xffff0000, v81
	v_lshlrev_b32_e32 v90, 16, v83
	v_and_b32_e32 v83, 0xffff0000, v83
	v_mul_f32_e32 v77, v77, v87
	v_mul_f32_e32 v79, v79, v80
	v_mul_f32_e32 v78, v78, v82
	v_mul_f32_e32 v80, v84, v88
	v_mul_f32_e32 v81, v86, v81
	v_mul_f32_e32 v84, v76, v89
	v_mul_f32_e32 v82, v85, v90
	v_mul_f32_e32 v83, v95, v83
	v_cvt_pk_bf16_f32 v76, v77, v79
	v_cvt_pk_bf16_f32 v77, v80, v81
	v_cvt_pk_bf16_f32 v78, v84, v78
	v_cvt_pk_bf16_f32 v79, v82, v83
	s_nop 0
	v_mfma_f32_16x16x32_bf16 v[68:71], v[148:151], v[76:79], v[68:71]
	v_mfma_f32_16x16x32_bf16 v[64:67], v[144:147], v[76:79], v[64:67]
	s_cbranch_vccnz .LBB0_348
	ds_read_b128 v[76:79], v172 offset:2304
	s_waitcnt lgkmcnt(0)
	v_lshlrev_b32_e32 v80, 16, v76
	v_and_b32_e32 v76, 0xffff0000, v76
	v_mul_f32_e32 v80, v103, v80
	v_mul_f32_e32 v76, v102, v76
	v_cvt_pk_bf16_f32 v76, v80, v76
	v_lshlrev_b32_e32 v80, 16, v77
	v_and_b32_e32 v77, 0xffff0000, v77
	v_mul_f32_e32 v80, v101, v80
	v_mul_f32_e32 v77, v100, v77
	v_cvt_pk_bf16_f32 v77, v80, v77
	v_lshlrev_b32_e32 v80, 16, v78
	v_and_b32_e32 v78, 0xffff0000, v78
	v_mul_f32_e32 v80, v96, v80
	v_mul_f32_e32 v78, v97, v78
	v_cvt_pk_bf16_f32 v78, v80, v78
	v_lshlrev_b32_e32 v80, 16, v79
	v_and_b32_e32 v79, 0xffff0000, v79
	v_mul_f32_e32 v79, v99, v79
	v_mul_f32_e32 v80, v98, v80
	v_cvt_pk_bf16_f32 v79, v80, v79
	s_nop 0
	v_mfma_f32_16x16x32_bf16 v[68:71], v[140:143], v[76:79], v[68:71]
	v_mfma_f32_16x16x32_bf16 v[64:67], v[136:139], v[76:79], v[64:67]

.LBB0_350:
	v_lshl_add_u32 v77, v233, 2, s32
	ds_read_b32 v77, v77 offset:192
	v_lshlrev_b32_e32 v78, 16, v75
	v_and_b32_e32 v75, 0xffff0000, v75
	v_add_u32_e32 v76, s94, v242
	s_or_b32 s16, s72, 1
	s_ashr_i32 s17, s16, 31
	s_lshl_b32 s26, s16, 7
	s_lshl_b64 s[16:17], s[16:17], 18
	s_ashr_i32 s27, s26, 31
	v_lshl_add_u64 v[88:89], s[26:27], 2, v[214:215]
	v_mov_b32_e32 v96, 0
	s_waitcnt lgkmcnt(0)
	v_fma_f32 v68, v116, v68, v77
	v_fma_f32 v69, v117, v69, v77
	v_mul_f32_e32 v68, v68, v78
	v_mul_f32_e32 v69, v69, v75
	v_cvt_pk_bf16_f32 v68, v68, v69
	v_lshlrev_b32_e32 v69, 16, v74
	v_fma_f32 v70, v118, v70, v77
	v_mul_f32_e32 v69, v70, v69
	v_and_b32_e32 v70, 0xffff0000, v74
	v_fma_f32 v71, v119, v71, v77
	v_mul_f32_e32 v70, v71, v70
	v_cvt_pk_bf16_f32 v69, v69, v70
	v_lshlrev_b32_e32 v70, 16, v73
	v_fma_f32 v64, v112, v64, v77
	v_mul_f32_e32 v64, v64, v70
	v_and_b32_e32 v70, 0xffff0000, v73
	v_fma_f32 v65, v113, v65, v77
	v_mul_f32_e32 v65, v65, v70
	v_cvt_pk_bf16_f32 v70, v64, v65
	v_lshlrev_b32_e32 v64, 16, v72
	v_fma_f32 v65, v114, v66, v77
	v_mul_f32_e32 v64, v65, v64
	v_and_b32_e32 v65, 0xffff0000, v72
	v_fmac_f32_e32 v77, v115, v67
	v_mul_f32_e32 v65, v77, v65
	v_ashrrev_i32_e32 v77, 31, v76
	v_cvt_pk_bf16_f32 v71, v64, v65
	v_lshlrev_b64 v[64:65], 12, v[76:77]
	v_lshl_add_u64 v[64:65], s[12:13], 0, v[64:65]
	v_lshl_add_u64 v[64:65], v[228:229], 1, v[64:65]
	global_store_dwordx4 v[64:65], v[68:71], off sc1
	v_lshl_add_u64 v[64:65], v[216:217], 0, s[16:17]
	v_lshl_add_u64 v[90:91], v[64:65], 0, s[40:41]
	v_add_co_u32_e32 v72, vcc, 0x1000, v90
	global_load_dwordx4 v[100:103], v[88:89], off offset:16
	global_load_dwordx4 v[104:107], v[88:89], off
	v_addc_co_u32_e32 v73, vcc, 0, v91, vcc
	global_load_dwordx4 v[64:67], v[90:91], off nt
	global_load_dwordx4 v[68:71], v[72:73], off nt
	global_load_dwordx4 v[128:131], v[88:89], off offset:144
	global_load_dwordx4 v[132:135], v[88:89], off offset:128
	global_load_dwordx4 v[80:83], v[90:91], off offset:1024 nt
	global_load_dwordx4 v[84:87], v[72:73], off offset:1024 nt
	s_and_b64 vcc, exec, s[8:9]
	s_cbranch_vccnz .LBB0_355
	v_add_co_u32_e32 v72, vcc, 0x1000, v90
	global_load_dwordx4 v[108:111], v[88:89], off offset:256
	global_load_dwordx4 v[124:127], v[88:89], off offset:272
	v_addc_co_u32_e32 v73, vcc, 0, v91, vcc
	global_load_dwordx4 v[76:79], v[90:91], off offset:2048 nt
	s_nop 0
	global_load_dwordx4 v[72:75], v[72:73], off offset:2048 nt
	s_and_b64 vcc, exec, s[8:9]
	s_cbranch_vccz .LBB0_356

.LBB0_363:
	v_lshl_add_u32 v56, v233, 2, s32
	ds_read_b32 v56, v56
	v_lshlrev_b32_e32 v57, 16, v55
	v_and_b32_e32 v55, 0xffff0000, v55
	v_lshlrev_b32_e32 v58, 16, v54
	v_and_b32_e32 v54, 0xffff0000, v54
	v_lshlrev_b32_e32 v59, 16, v53
	v_and_b32_e32 v60, 0xffff0000, v53
	v_lshlrev_b32_e32 v61, 16, v52
	v_and_b32_e32 v62, 0xffff0000, v52
	s_or_b32 s40, s94, 0x80
	v_add_u32_e32 v52, s40, v234
	v_ashrrev_i32_e32 v53, 31, v52
	v_lshlrev_b64 v[52:53], 12, v[52:53]
	v_lshl_add_u64 v[52:53], s[12:13], 0, v[52:53]
	v_lshl_add_u64 v[52:53], v[228:229], 1, v[52:53]
	s_and_b64 vcc, exec, s[8:9]
	s_waitcnt vmcnt(0) lgkmcnt(0)
	v_fma_f32 v0, v116, v0, v56
	v_fma_f32 v1, v117, v1, v56
	v_fma_f32 v2, v118, v2, v56
	v_fma_f32 v3, v119, v3, v56
	v_fma_f32 v4, v112, v4, v56
	v_fma_f32 v5, v113, v5, v56
	v_fma_f32 v6, v114, v6, v56
	v_fmac_f32_e32 v56, v115, v7
	v_mul_f32_e32 v0, v0, v57
	v_mul_f32_e32 v1, v1, v55
	v_mul_f32_e32 v2, v2, v58
	v_mul_f32_e32 v3, v3, v54
	v_mul_f32_e32 v4, v4, v59
	v_mul_f32_e32 v5, v5, v60
	v_mul_f32_e32 v6, v6, v61
	v_mul_f32_e32 v7, v56, v62
	v_cvt_pk_bf16_f32 v0, v0, v1
	v_cvt_pk_bf16_f32 v1, v2, v3
	v_cvt_pk_bf16_f32 v2, v4, v5
	v_cvt_pk_bf16_f32 v3, v6, v7
	ds_read_b128 v[4:7], v171 offset:256
	global_store_dwordx4 v[52:53], v[0:3], off sc1
	s_waitcnt lgkmcnt(0)
	s_nop 0
	v_lshlrev_b32_e32 v0, 16, v4
	v_and_b32_e32 v1, 0xffff0000, v4
	v_lshlrev_b32_e32 v2, 16, v5
	v_and_b32_e32 v3, 0xffff0000, v5
	v_lshlrev_b32_e32 v4, 16, v6
	v_and_b32_e32 v5, 0xffff0000, v6
	v_lshlrev_b32_e32 v6, 16, v7
	v_and_b32_e32 v7, 0xffff0000, v7
	v_mul_f32_e32 v0, v24, v0
	v_mul_f32_e32 v1, v26, v1
	v_mul_f32_e32 v2, v28, v2
	v_mul_f32_e32 v3, v30, v3
	v_mul_f32_e32 v4, v23, v4
	v_mul_f32_e32 v5, v25, v5
	v_mul_f32_e32 v6, v27, v6
	v_mul_f32_e32 v7, v29, v7
	v_cvt_pk_bf16_f32 v0, v0, v1
	v_cvt_pk_bf16_f32 v1, v2, v3
	v_cvt_pk_bf16_f32 v2, v4, v5
	v_cvt_pk_bf16_f32 v3, v6, v7
	s_nop 0
	v_mfma_f32_16x16x32_bf16 v[4:7], v[64:67], v[0:3], 0
	v_mfma_f32_16x16x32_bf16 v[0:3], v[68:71], v[0:3], 0
	s_cbranch_vccz .LBB0_378
	s_and_b64 vcc, exec, s[8:9]
	s_cbranch_vccz .LBB0_379

.LBB0_367:
	v_lshl_add_u32 v53, v233, 2, s32
	ds_read_b32 v53, v53 offset:64
	v_lshlrev_b32_e32 v54, 16, v51
	v_and_b32_e32 v51, 0xffff0000, v51
	v_add_u32_e32 v52, s40, v240
	s_and_b64 vcc, exec, s[8:9]
	s_waitcnt lgkmcnt(0)
	s_nop 0
	v_fma_f32 v4, v116, v4, v53
	v_fma_f32 v5, v117, v5, v53
	v_mul_f32_e32 v4, v4, v54
	v_mul_f32_e32 v5, v5, v51
	v_cvt_pk_bf16_f32 v4, v4, v5
	v_lshlrev_b32_e32 v5, 16, v50
	v_fma_f32 v6, v118, v6, v53
	v_mul_f32_e32 v5, v6, v5
	v_and_b32_e32 v6, 0xffff0000, v50
	v_fma_f32 v7, v119, v7, v53
	v_mul_f32_e32 v6, v7, v6
	v_cvt_pk_bf16_f32 v5, v5, v6
	v_lshlrev_b32_e32 v6, 16, v49
	v_fma_f32 v0, v112, v0, v53
	v_mul_f32_e32 v0, v0, v6
	v_and_b32_e32 v6, 0xffff0000, v49
	v_fma_f32 v1, v113, v1, v53
	v_mul_f32_e32 v1, v1, v6
	v_cvt_pk_bf16_f32 v6, v0, v1
	v_lshlrev_b32_e32 v0, 16, v48
	v_fma_f32 v1, v114, v2, v53
	v_mul_f32_e32 v0, v1, v0
	v_and_b32_e32 v1, 0xffff0000, v48
	v_fmac_f32_e32 v53, v115, v3
	v_mul_f32_e32 v1, v53, v1
	v_ashrrev_i32_e32 v53, 31, v52
	v_cvt_pk_bf16_f32 v7, v0, v1
	v_lshlrev_b64 v[0:1], 12, v[52:53]
	v_lshl_add_u64 v[0:1], s[12:13], 0, v[0:1]
	v_lshl_add_u64 v[0:1], v[228:229], 1, v[0:1]
	global_store_dwordx4 v[0:1], v[4:7], off sc1
	ds_read_b128 v[0:3], v170
	s_waitcnt lgkmcnt(0)
	v_lshlrev_b32_e32 v4, 16, v0
	v_and_b32_e32 v0, 0xffff0000, v0
	v_mul_f32_e32 v4, v24, v4
	v_mul_f32_e32 v0, v26, v0
	v_cvt_pk_bf16_f32 v0, v4, v0
	v_lshlrev_b32_e32 v4, 16, v1
	v_and_b32_e32 v1, 0xffff0000, v1
	v_mul_f32_e32 v4, v28, v4
	v_mul_f32_e32 v1, v30, v1
	v_cvt_pk_bf16_f32 v1, v4, v1
	v_lshlrev_b32_e32 v4, 16, v2
	v_and_b32_e32 v2, 0xffff0000, v2
	v_mul_f32_e32 v4, v23, v4
	v_mul_f32_e32 v2, v25, v2
	v_cvt_pk_bf16_f32 v2, v4, v2
	v_lshlrev_b32_e32 v4, 16, v3
	v_and_b32_e32 v3, 0xffff0000, v3
	v_mul_f32_e32 v3, v29, v3
	v_mul_f32_e32 v4, v27, v4
	v_cvt_pk_bf16_f32 v3, v4, v3
	ds_read_b128 v[48:51], v170 offset:1024
	v_mfma_f32_16x16x32_bf16 v[4:7], v[64:67], v[0:3], 0
	s_waitcnt lgkmcnt(0)
	v_lshlrev_b32_e32 v52, 16, v48
	v_and_b32_e32 v48, 0xffff0000, v48
	v_mul_f32_e32 v52, v13, v52
	v_mul_f32_e32 v48, v15, v48
	v_cvt_pk_bf16_f32 v48, v52, v48
	v_lshlrev_b32_e32 v52, 16, v49
	v_and_b32_e32 v49, 0xffff0000, v49
	v_mul_f32_e32 v52, v20, v52
	v_mul_f32_e32 v49, v22, v49
	v_mfma_f32_16x16x32_bf16 v[0:3], v[68:71], v[0:3], 0
	v_cvt_pk_bf16_f32 v49, v52, v49
	v_lshlrev_b32_e32 v52, 16, v50
	v_and_b32_e32 v50, 0xffff0000, v50
	v_mul_f32_e32 v52, v12, v52
	v_mul_f32_e32 v50, v14, v50
	v_cvt_pk_bf16_f32 v50, v52, v50
	v_lshlrev_b32_e32 v52, 16, v51
	v_and_b32_e32 v51, 0xffff0000, v51
	v_mul_f32_e32 v51, v31, v51
	v_mul_f32_e32 v52, v21, v52
	v_cvt_pk_bf16_f32 v51, v52, v51
	s_nop 0
	v_mfma_f32_16x16x32_bf16 v[4:7], v[80:83], v[48:51], v[4:7]
	v_mfma_f32_16x16x32_bf16 v[0:3], v[84:87], v[48:51], v[0:3]
	s_cbranch_vccnz .LBB0_369
	ds_read_b128 v[48:51], v170 offset:2048
	s_waitcnt lgkmcnt(0)
	v_lshlrev_b32_e32 v52, 16, v48
	v_and_b32_e32 v48, 0xffff0000, v48
	v_mul_f32_e32 v52, v39, v52
	v_mul_f32_e32 v48, v38, v48
	v_cvt_pk_bf16_f32 v48, v52, v48
	v_lshlrev_b32_e32 v52, 16, v49
	v_and_b32_e32 v49, 0xffff0000, v49
	v_mul_f32_e32 v52, v37, v52
	v_mul_f32_e32 v49, v36, v49
	v_cvt_pk_bf16_f32 v49, v52, v49
	v_lshlrev_b32_e32 v52, 16, v50
	v_and_b32_e32 v50, 0xffff0000, v50
	v_mul_f32_e32 v52, v32, v52
	v_mul_f32_e32 v50, v33, v50
	v_cvt_pk_bf16_f32 v50, v52, v50
	v_lshlrev_b32_e32 v52, 16, v51
	v_and_b32_e32 v51, 0xffff0000, v51
	v_mul_f32_e32 v51, v35, v51
	v_mul_f32_e32 v52, v34, v52
	v_cvt_pk_bf16_f32 v51, v52, v51
	s_nop 0
	v_mfma_f32_16x16x32_bf16 v[4:7], v[76:79], v[48:51], v[4:7]
	v_mfma_f32_16x16x32_bf16 v[0:3], v[72:75], v[48:51], v[0:3]

.LBB0_371:
	v_lshl_add_u32 v50, v233, 2, s32
	ds_read_b32 v50, v50 offset:128
	v_lshlrev_b32_e32 v51, 16, v19
	v_and_b32_e32 v19, 0xffff0000, v19
	v_lshlrev_b32_e32 v52, 16, v18
	v_and_b32_e32 v18, 0xffff0000, v18
	v_lshlrev_b32_e32 v53, 16, v17
	v_and_b32_e32 v17, 0xffff0000, v17
	v_lshlrev_b32_e32 v54, 16, v16
	v_and_b32_e32 v16, 0xffff0000, v16
	v_add_u32_e32 v48, s40, v241
	v_ashrrev_i32_e32 v49, 31, v48
	s_and_b64 vcc, exec, s[8:9]
	s_waitcnt lgkmcnt(0)
	v_fma_f32 v4, v116, v4, v50
	v_fma_f32 v5, v117, v5, v50
	v_fma_f32 v6, v118, v6, v50
	v_fma_f32 v7, v119, v7, v50
	v_fma_f32 v0, v112, v0, v50
	v_fma_f32 v1, v113, v1, v50
	v_fma_f32 v2, v114, v2, v50
	v_fmac_f32_e32 v50, v115, v3
	v_mul_f32_e32 v3, v4, v51
	v_mul_f32_e32 v4, v5, v19
	v_mul_f32_e32 v5, v6, v52
	v_mul_f32_e32 v6, v7, v18
	v_mul_f32_e32 v7, v0, v53
	v_mul_f32_e32 v17, v1, v17
	v_mul_f32_e32 v18, v2, v54
	v_mul_f32_e32 v16, v50, v16
	v_cvt_pk_bf16_f32 v0, v3, v4
	v_cvt_pk_bf16_f32 v1, v5, v6
	v_cvt_pk_bf16_f32 v2, v7, v17
	v_cvt_pk_bf16_f32 v3, v18, v16
	ds_read_b128 v[4:7], v172 offset:256
	v_lshlrev_b64 v[16:17], 12, v[48:49]
	v_lshl_add_u64 v[16:17], s[12:13], 0, v[16:17]
	v_lshl_add_u64 v[16:17], v[228:229], 1, v[16:17]
	global_store_dwordx4 v[16:17], v[0:3], off sc1
	s_waitcnt lgkmcnt(0)
	s_nop 0
	v_lshlrev_b32_e32 v0, 16, v4
	v_and_b32_e32 v1, 0xffff0000, v4
	v_lshlrev_b32_e32 v2, 16, v5
	v_and_b32_e32 v3, 0xffff0000, v5
	v_lshlrev_b32_e32 v4, 16, v6
	v_and_b32_e32 v5, 0xffff0000, v6
	v_lshlrev_b32_e32 v6, 16, v7
	v_and_b32_e32 v7, 0xffff0000, v7
	v_mul_f32_e32 v0, v24, v0
	v_mul_f32_e32 v1, v26, v1
	v_mul_f32_e32 v2, v28, v2
	v_mul_f32_e32 v3, v30, v3
	v_mul_f32_e32 v4, v23, v4
	v_mul_f32_e32 v5, v25, v5
	v_mul_f32_e32 v6, v27, v6
	v_mul_f32_e32 v7, v29, v7
	v_cvt_pk_bf16_f32 v0, v0, v1
	v_cvt_pk_bf16_f32 v1, v2, v3
	v_cvt_pk_bf16_f32 v2, v4, v5
	v_cvt_pk_bf16_f32 v3, v6, v7
	ds_read_b128 v[16:19], v172 offset:1280
	v_mfma_f32_16x16x32_bf16 v[4:7], v[64:67], v[0:3], 0
	s_waitcnt lgkmcnt(0)
	v_lshlrev_b32_e32 v23, 16, v16
	v_mfma_f32_16x16x32_bf16 v[0:3], v[68:71], v[0:3], 0
	v_and_b32_e32 v16, 0xffff0000, v16
	v_lshlrev_b32_e32 v25, 16, v18
	v_and_b32_e32 v18, 0xffff0000, v18
	v_lshlrev_b32_e32 v24, 16, v17
	v_and_b32_e32 v17, 0xffff0000, v17
	v_lshlrev_b32_e32 v26, 16, v19
	v_and_b32_e32 v19, 0xffff0000, v19
	v_mul_f32_e32 v13, v13, v23
	v_mul_f32_e32 v15, v15, v16
	v_mul_f32_e32 v14, v14, v18
	v_mul_f32_e32 v16, v20, v24
	v_mul_f32_e32 v17, v22, v17
	v_mul_f32_e32 v20, v12, v25
	v_mul_f32_e32 v18, v21, v26
	v_mul_f32_e32 v19, v31, v19
	v_cvt_pk_bf16_f32 v12, v13, v15
	v_cvt_pk_bf16_f32 v13, v16, v17
	v_cvt_pk_bf16_f32 v14, v20, v14
	v_cvt_pk_bf16_f32 v15, v18, v19
	s_nop 0
	v_mfma_f32_16x16x32_bf16 v[4:7], v[80:83], v[12:15], v[4:7]
	v_mfma_f32_16x16x32_bf16 v[0:3], v[84:87], v[12:15], v[0:3]
	s_cbranch_vccnz .LBB0_373
	ds_read_b128 v[12:15], v172 offset:2304
	s_waitcnt lgkmcnt(0)
	v_lshlrev_b32_e32 v16, 16, v12
	v_and_b32_e32 v12, 0xffff0000, v12
	v_mul_f32_e32 v16, v39, v16
	v_mul_f32_e32 v12, v38, v12
	v_cvt_pk_bf16_f32 v12, v16, v12
	v_lshlrev_b32_e32 v16, 16, v13
	v_and_b32_e32 v13, 0xffff0000, v13
	v_mul_f32_e32 v16, v37, v16
	v_mul_f32_e32 v13, v36, v13
	v_cvt_pk_bf16_f32 v13, v16, v13
	v_lshlrev_b32_e32 v16, 16, v14
	v_and_b32_e32 v14, 0xffff0000, v14
	v_mul_f32_e32 v16, v32, v16
	v_mul_f32_e32 v14, v33, v14
	v_cvt_pk_bf16_f32 v14, v16, v14
	v_lshlrev_b32_e32 v16, 16, v15
	v_and_b32_e32 v15, 0xffff0000, v15
	v_mul_f32_e32 v15, v35, v15
	v_mul_f32_e32 v16, v34, v16
	v_cvt_pk_bf16_f32 v15, v16, v15
	s_nop 0
	v_mfma_f32_16x16x32_bf16 v[4:7], v[76:79], v[12:15], v[4:7]
	v_mfma_f32_16x16x32_bf16 v[0:3], v[72:75], v[12:15], v[0:3]

.LBB0_375:
	v_lshl_add_u32 v14, v233, 2, s32
	ds_read_b32 v14, v14 offset:192
	v_add_u32_e32 v12, s40, v242
	v_ashrrev_i32_e32 v13, 31, v12
	v_lshlrev_b32_e32 v15, 16, v11
	v_and_b32_e32 v11, 0xffff0000, v11
	v_lshlrev_b32_e32 v16, 16, v10
	v_lshlrev_b32_e32 v17, 16, v9
	v_and_b32_e32 v18, 0xffff0000, v9
	v_lshlrev_b32_e32 v19, 16, v8
	v_and_b32_e32 v20, 0xffff0000, v8
	v_lshlrev_b64 v[8:9], 12, v[12:13]
	v_and_b32_e32 v10, 0xffff0000, v10
	v_lshl_add_u64 v[8:9], s[12:13], 0, v[8:9]
	s_waitcnt lgkmcnt(0)
	v_fma_f32 v4, v116, v4, v14
	v_fma_f32 v5, v117, v5, v14
	v_fma_f32 v6, v118, v6, v14
	v_fma_f32 v7, v119, v7, v14
	v_fma_f32 v0, v112, v0, v14
	v_fma_f32 v1, v113, v1, v14
	v_fma_f32 v2, v114, v2, v14
	v_fmac_f32_e32 v14, v115, v3
	v_mul_f32_e32 v3, v4, v15
	v_mul_f32_e32 v4, v5, v11
	v_mul_f32_e32 v5, v6, v16
	v_mul_f32_e32 v6, v7, v10
	v_mul_f32_e32 v7, v0, v17
	v_mul_f32_e32 v10, v1, v18
	v_cvt_pk_bf16_f32 v0, v3, v4
	v_cvt_pk_bf16_f32 v1, v5, v6
	v_lshl_add_u64 v[4:5], v[228:229], 1, v[8:9]
	v_mul_f32_e32 v11, v2, v19
	v_mul_f32_e32 v12, v14, v20
	v_cvt_pk_bf16_f32 v2, v7, v10
	v_cvt_pk_bf16_f32 v3, v11, v12
	global_store_dwordx4 v[4:5], v[0:3], off sc1
	s_andn2_b64 vcc, exec, s[6:7]
	s_mov_b64 s[6:7], -1
	s_cbranch_vccnz .LBB0_298
